# P0 adaLN items: silu(c) staging with all 32 loads in flight instead of one round trip per value
# baseline (speedup 1.0000x reference)
; __device__ __forceinline__ float sigm(float x) { return __builtin_amdgcn_rcpf(1.0f + __builtin_amdgcn_exp2f(-1.4426950408889634f * x)); }
; __device__ __forceinline__ float sigm(float x) { return rcp(1.0f + ex2(-LOG2E * x)); }
; __device__ __forceinline__ void phase0(const Params& p, LAS unsigned char* lds, int tid, int lane, int wave) {
;     ...
;             const float* c = p.in[1]; const float* ada_w = p.in[3]; const float* ada_b = p.in[4];
;             for (int e = tid; e < 16384; e += 512) { const float v = c[e]; sc[e] = v * sigm(v); }
;             __syncthreads();
.LBB0_75:
	s_and_saveexec_b64 s[12:13], s[6:7]
	s_cbranch_execz .LBB0_78
	s_mov_b64 s[40:41], 0
	v_mov_b64_e32 v[6:7], v[24:25]
	s_mov_b64 s[42:43], 0x800
	global_load_dword v28, v[6:7], off
	v_lshl_add_u64 v[6:7], v[6:7], 0, s[42:43]
	global_load_dword v29, v[6:7], off
	v_lshl_add_u64 v[6:7], v[6:7], 0, s[42:43]
	global_load_dword v30, v[6:7], off
	v_lshl_add_u64 v[6:7], v[6:7], 0, s[42:43]
	global_load_dword v31, v[6:7], off
	v_lshl_add_u64 v[6:7], v[6:7], 0, s[42:43]
	global_load_dword v32, v[6:7], off
	v_lshl_add_u64 v[6:7], v[6:7], 0, s[42:43]
	global_load_dword v33, v[6:7], off
	v_lshl_add_u64 v[6:7], v[6:7], 0, s[42:43]
	global_load_dword v34, v[6:7], off
	v_lshl_add_u64 v[6:7], v[6:7], 0, s[42:43]
	global_load_dword v35, v[6:7], off
	v_lshl_add_u64 v[6:7], v[6:7], 0, s[42:43]
	global_load_dword v36, v[6:7], off
	v_lshl_add_u64 v[6:7], v[6:7], 0, s[42:43]
	global_load_dword v37, v[6:7], off
	v_lshl_add_u64 v[6:7], v[6:7], 0, s[42:43]
	global_load_dword v38, v[6:7], off
	v_lshl_add_u64 v[6:7], v[6:7], 0, s[42:43]
	global_load_dword v39, v[6:7], off
	v_lshl_add_u64 v[6:7], v[6:7], 0, s[42:43]
	global_load_dword v40, v[6:7], off
	v_lshl_add_u64 v[6:7], v[6:7], 0, s[42:43]
	global_load_dword v41, v[6:7], off
	v_lshl_add_u64 v[6:7], v[6:7], 0, s[42:43]
	global_load_dword v42, v[6:7], off
	v_lshl_add_u64 v[6:7], v[6:7], 0, s[42:43]
	global_load_dword v43, v[6:7], off
	v_lshl_add_u64 v[6:7], v[6:7], 0, s[42:43]
	global_load_dword v44, v[6:7], off
	v_lshl_add_u64 v[6:7], v[6:7], 0, s[42:43]
	global_load_dword v45, v[6:7], off
	v_lshl_add_u64 v[6:7], v[6:7], 0, s[42:43]
	global_load_dword v46, v[6:7], off
	v_lshl_add_u64 v[6:7], v[6:7], 0, s[42:43]
	global_load_dword v47, v[6:7], off
	v_lshl_add_u64 v[6:7], v[6:7], 0, s[42:43]
	global_load_dword v48, v[6:7], off
	v_lshl_add_u64 v[6:7], v[6:7], 0, s[42:43]
	global_load_dword v49, v[6:7], off
	v_lshl_add_u64 v[6:7], v[6:7], 0, s[42:43]
	global_load_dword v50, v[6:7], off
	v_lshl_add_u64 v[6:7], v[6:7], 0, s[42:43]
	global_load_dword v51, v[6:7], off
	v_lshl_add_u64 v[6:7], v[6:7], 0, s[42:43]
	global_load_dword v52, v[6:7], off
	v_lshl_add_u64 v[6:7], v[6:7], 0, s[42:43]
	global_load_dword v53, v[6:7], off
	v_lshl_add_u64 v[6:7], v[6:7], 0, s[42:43]
	global_load_dword v54, v[6:7], off
	v_lshl_add_u64 v[6:7], v[6:7], 0, s[42:43]
	global_load_dword v55, v[6:7], off
	v_lshl_add_u64 v[6:7], v[6:7], 0, s[42:43]
	global_load_dword v56, v[6:7], off
	v_lshl_add_u64 v[6:7], v[6:7], 0, s[42:43]
	global_load_dword v57, v[6:7], off
	v_lshl_add_u64 v[6:7], v[6:7], 0, s[42:43]
	global_load_dword v58, v[6:7], off
	v_lshl_add_u64 v[6:7], v[6:7], 0, s[42:43]
	global_load_dword v59, v[6:7], off
	v_mov_b32_e32 v8, v82
	s_waitcnt vmcnt(28)
	v_mul_f32_e32 v60, 0xbfb8aa3b, v28
	v_mul_f32_e32 v61, 0xbfb8aa3b, v29
	v_mul_f32_e32 v62, 0xbfb8aa3b, v30
	v_mul_f32_e32 v63, 0xbfb8aa3b, v31
	v_exp_f32_e32 v60, v60
	v_exp_f32_e32 v61, v61
	v_exp_f32_e32 v62, v62
	v_exp_f32_e32 v63, v63
	v_add_f32_e32 v60, 1.0, v60
	v_add_f32_e32 v61, 1.0, v61
	v_add_f32_e32 v62, 1.0, v62
	v_add_f32_e32 v63, 1.0, v63
	v_rcp_f32_e32 v60, v60
	v_rcp_f32_e32 v61, v61
	v_rcp_f32_e32 v62, v62
	v_rcp_f32_e32 v63, v63
	v_mul_f32_e32 v28, v28, v60
	v_mul_f32_e32 v29, v29, v61
	v_mul_f32_e32 v30, v30, v62
	v_mul_f32_e32 v31, v31, v63
	ds_write_b32 v8, v28
	v_add_u32_e32 v8, 0x800, v8
	ds_write_b32 v8, v29
	v_add_u32_e32 v8, 0x800, v8
	ds_write_b32 v8, v30
	v_add_u32_e32 v8, 0x800, v8
	ds_write_b32 v8, v31
	v_add_u32_e32 v8, 0x800, v8
	s_waitcnt vmcnt(24)
	v_mul_f32_e32 v60, 0xbfb8aa3b, v32
	v_mul_f32_e32 v61, 0xbfb8aa3b, v33
	v_mul_f32_e32 v62, 0xbfb8aa3b, v34
	v_mul_f32_e32 v63, 0xbfb8aa3b, v35
	v_exp_f32_e32 v60, v60
	v_exp_f32_e32 v61, v61
	v_exp_f32_e32 v62, v62
	v_exp_f32_e32 v63, v63
	v_add_f32_e32 v60, 1.0, v60
	v_add_f32_e32 v61, 1.0, v61
	v_add_f32_e32 v62, 1.0, v62
	v_add_f32_e32 v63, 1.0, v63
	v_rcp_f32_e32 v60, v60
	v_rcp_f32_e32 v61, v61
	v_rcp_f32_e32 v62, v62
	v_rcp_f32_e32 v63, v63
	v_mul_f32_e32 v32, v32, v60
	v_mul_f32_e32 v33, v33, v61
	v_mul_f32_e32 v34, v34, v62
	v_mul_f32_e32 v35, v35, v63
	ds_write_b32 v8, v32
	v_add_u32_e32 v8, 0x800, v8
	ds_write_b32 v8, v33
	v_add_u32_e32 v8, 0x800, v8
	ds_write_b32 v8, v34
	v_add_u32_e32 v8, 0x800, v8
	ds_write_b32 v8, v35
	v_add_u32_e32 v8, 0x800, v8
	s_waitcnt vmcnt(20)
; __device__ __forceinline__ float sigm(float x) { return __builtin_amdgcn_rcpf(1.0f + __builtin_amdgcn_exp2f(-1.4426950408889634f * x)); }
; __device__ __forceinline__ float sigm(float x) { return rcp(1.0f + ex2(-LOG2E * x)); }
; __device__ __forceinline__ void phase0(const Params& p, LAS unsigned char* lds, int tid, int lane, int wave) {
;     ...
;             for (int e = tid; e < 16384; e += 512) { const float v = c[e]; sc[e] = v * sigm(v); }
	v_mul_f32_e32 v60, 0xbfb8aa3b, v36
	v_mul_f32_e32 v61, 0xbfb8aa3b, v37
	v_mul_f32_e32 v62, 0xbfb8aa3b, v38
	v_mul_f32_e32 v63, 0xbfb8aa3b, v39
	v_exp_f32_e32 v60, v60
	v_exp_f32_e32 v61, v61
	v_exp_f32_e32 v62, v62
	v_exp_f32_e32 v63, v63
	v_add_f32_e32 v60, 1.0, v60
	v_add_f32_e32 v61, 1.0, v61
	v_add_f32_e32 v62, 1.0, v62
	v_add_f32_e32 v63, 1.0, v63
	v_rcp_f32_e32 v60, v60
	v_rcp_f32_e32 v61, v61
	v_rcp_f32_e32 v62, v62
	v_rcp_f32_e32 v63, v63
	v_mul_f32_e32 v36, v36, v60
	v_mul_f32_e32 v37, v37, v61
	v_mul_f32_e32 v38, v38, v62
	v_mul_f32_e32 v39, v39, v63
	ds_write_b32 v8, v36
	v_add_u32_e32 v8, 0x800, v8
	ds_write_b32 v8, v37
	v_add_u32_e32 v8, 0x800, v8
	ds_write_b32 v8, v38
	v_add_u32_e32 v8, 0x800, v8
	ds_write_b32 v8, v39
	v_add_u32_e32 v8, 0x800, v8
	s_waitcnt vmcnt(16)
	v_mul_f32_e32 v60, 0xbfb8aa3b, v40
	v_mul_f32_e32 v61, 0xbfb8aa3b, v41
	v_mul_f32_e32 v62, 0xbfb8aa3b, v42
	v_mul_f32_e32 v63, 0xbfb8aa3b, v43
	v_exp_f32_e32 v60, v60
	v_exp_f32_e32 v61, v61
	v_exp_f32_e32 v62, v62
	v_exp_f32_e32 v63, v63
	v_add_f32_e32 v60, 1.0, v60
	v_add_f32_e32 v61, 1.0, v61
	v_add_f32_e32 v62, 1.0, v62
	v_add_f32_e32 v63, 1.0, v63
	v_rcp_f32_e32 v60, v60
	v_rcp_f32_e32 v61, v61
	v_rcp_f32_e32 v62, v62
	v_rcp_f32_e32 v63, v63
	v_mul_f32_e32 v40, v40, v60
	v_mul_f32_e32 v41, v41, v61
	v_mul_f32_e32 v42, v42, v62
	v_mul_f32_e32 v43, v43, v63
	ds_write_b32 v8, v40
	v_add_u32_e32 v8, 0x800, v8
	ds_write_b32 v8, v41
	v_add_u32_e32 v8, 0x800, v8
	ds_write_b32 v8, v42
	v_add_u32_e32 v8, 0x800, v8
	ds_write_b32 v8, v43
	v_add_u32_e32 v8, 0x800, v8
	s_waitcnt vmcnt(12)
	v_mul_f32_e32 v60, 0xbfb8aa3b, v44
	v_mul_f32_e32 v61, 0xbfb8aa3b, v45
	v_mul_f32_e32 v62, 0xbfb8aa3b, v46
	v_mul_f32_e32 v63, 0xbfb8aa3b, v47
	v_exp_f32_e32 v60, v60
	v_exp_f32_e32 v61, v61
	v_exp_f32_e32 v62, v62
	v_exp_f32_e32 v63, v63
	v_add_f32_e32 v60, 1.0, v60
	v_add_f32_e32 v61, 1.0, v61
	v_add_f32_e32 v62, 1.0, v62
	v_add_f32_e32 v63, 1.0, v63
	v_rcp_f32_e32 v60, v60
	v_rcp_f32_e32 v61, v61
	v_rcp_f32_e32 v62, v62
	v_rcp_f32_e32 v63, v63
	v_mul_f32_e32 v44, v44, v60
	v_mul_f32_e32 v45, v45, v61
	v_mul_f32_e32 v46, v46, v62
	v_mul_f32_e32 v47, v47, v63
	ds_write_b32 v8, v44
	v_add_u32_e32 v8, 0x800, v8
	ds_write_b32 v8, v45
	v_add_u32_e32 v8, 0x800, v8
	ds_write_b32 v8, v46
	v_add_u32_e32 v8, 0x800, v8
	ds_write_b32 v8, v47
	v_add_u32_e32 v8, 0x800, v8
	s_waitcnt vmcnt(8)
	v_mul_f32_e32 v60, 0xbfb8aa3b, v48
	v_mul_f32_e32 v61, 0xbfb8aa3b, v49
	v_mul_f32_e32 v62, 0xbfb8aa3b, v50
	v_mul_f32_e32 v63, 0xbfb8aa3b, v51
	v_exp_f32_e32 v60, v60
	v_exp_f32_e32 v61, v61
	v_exp_f32_e32 v62, v62
	v_exp_f32_e32 v63, v63
	v_add_f32_e32 v60, 1.0, v60
	v_add_f32_e32 v61, 1.0, v61
	v_add_f32_e32 v62, 1.0, v62
	v_add_f32_e32 v63, 1.0, v63
	v_rcp_f32_e32 v60, v60
	v_rcp_f32_e32 v61, v61
	v_rcp_f32_e32 v62, v62
	v_rcp_f32_e32 v63, v63
	v_mul_f32_e32 v48, v48, v60
	v_mul_f32_e32 v49, v49, v61
	v_mul_f32_e32 v50, v50, v62
	v_mul_f32_e32 v51, v51, v63
	ds_write_b32 v8, v48
	v_add_u32_e32 v8, 0x800, v8
	ds_write_b32 v8, v49
	v_add_u32_e32 v8, 0x800, v8
	ds_write_b32 v8, v50
	v_add_u32_e32 v8, 0x800, v8
	ds_write_b32 v8, v51
	v_add_u32_e32 v8, 0x800, v8
	s_waitcnt vmcnt(4)
	v_mul_f32_e32 v60, 0xbfb8aa3b, v52
	v_mul_f32_e32 v61, 0xbfb8aa3b, v53
	v_mul_f32_e32 v62, 0xbfb8aa3b, v54
	v_mul_f32_e32 v63, 0xbfb8aa3b, v55
	v_exp_f32_e32 v60, v60
	v_exp_f32_e32 v61, v61
	v_exp_f32_e32 v62, v62
	v_exp_f32_e32 v63, v63
	v_add_f32_e32 v60, 1.0, v60
	v_add_f32_e32 v61, 1.0, v61
	v_add_f32_e32 v62, 1.0, v62
	v_add_f32_e32 v63, 1.0, v63
	v_rcp_f32_e32 v60, v60
	v_rcp_f32_e32 v61, v61
	v_rcp_f32_e32 v62, v62
	v_rcp_f32_e32 v63, v63
	v_mul_f32_e32 v52, v52, v60
	v_mul_f32_e32 v53, v53, v61
	v_mul_f32_e32 v54, v54, v62
	v_mul_f32_e32 v55, v55, v63
	ds_write_b32 v8, v52
	v_add_u32_e32 v8, 0x800, v8
	ds_write_b32 v8, v53
	v_add_u32_e32 v8, 0x800, v8
	ds_write_b32 v8, v54
	v_add_u32_e32 v8, 0x800, v8
	ds_write_b32 v8, v55
	v_add_u32_e32 v8, 0x800, v8
	s_waitcnt vmcnt(0)
	v_mul_f32_e32 v60, 0xbfb8aa3b, v56
	v_mul_f32_e32 v61, 0xbfb8aa3b, v57
	v_mul_f32_e32 v62, 0xbfb8aa3b, v58
	v_mul_f32_e32 v63, 0xbfb8aa3b, v59
	v_exp_f32_e32 v60, v60
	v_exp_f32_e32 v61, v61
	v_exp_f32_e32 v62, v62
	v_exp_f32_e32 v63, v63
	v_add_f32_e32 v60, 1.0, v60
	v_add_f32_e32 v61, 1.0, v61
	v_add_f32_e32 v62, 1.0, v62
	v_add_f32_e32 v63, 1.0, v63
	v_rcp_f32_e32 v60, v60
	v_rcp_f32_e32 v61, v61
	v_rcp_f32_e32 v62, v62
	v_rcp_f32_e32 v63, v63
	v_mul_f32_e32 v56, v56, v60
	v_mul_f32_e32 v57, v57, v61
	v_mul_f32_e32 v58, v58, v62
	v_mul_f32_e32 v59, v59, v63
	ds_write_b32 v8, v56
	v_add_u32_e32 v8, 0x800, v8
	ds_write_b32 v8, v57
	v_add_u32_e32 v8, 0x800, v8
	ds_write_b32 v8, v58
	v_add_u32_e32 v8, 0x800, v8
	ds_write_b32 v8, v59
	v_add_u32_e32 v8, 0x800, v8
